# P1/P5: all LDS-DMA loads confirmed (vmcnt(0)) at epilogue start and prologue end, first two counted waits of each unit dropped so the first MFMA blocks do not wait for store acks
# baseline (speedup 1.0000x reference)
.LBB0_172:
	s_add_u32 s4, s50, 0x4000000
	s_addc_u32 s5, s51, 0
	s_add_u32 s6, s50, 0x4800000
	v_readlane_b32 s8, v245, 9
	s_addc_u32 s7, s51, 0
	s_lshl_b32 s8, s8, 2
	s_add_u32 s8, s70, s8
	s_addc_u32 s9, s71, 0
	s_add_u32 s8, s8, 0xa0000
	s_addc_u32 s9, s9, 0
	s_lshl_b32 s10, s10, 5
	s_and_b32 s19, s10, 0x60
	s_mov_b64 s[10:11], 0x80
	s_add_i32 m0, s43, 0x18000
	v_lshl_add_u64 v[8:9], v[8:9], 0, s[10:11]
	s_lshl_b32 s13, s18, 13
	s_lshl_b32 s22, s19, 7
	s_waitcnt vmcnt(2)
	s_barrier
	global_load_lds_dwordx4 v[8:9], off
	v_lshl_add_u64 v[6:7], v[6:7], 0, s[10:11]
	s_add_i32 m0, s43, 0x1a000
	s_add_i32 s57, s43, 0x8000
	s_add_i32 s58, s43, 0xa000
	global_load_lds_dwordx4 v[6:7], off
	v_lshl_add_u64 v[2:3], v[2:3], 0, s[10:11]
	s_mov_b32 m0, s57
	s_add_u32 s20, s44, 0x40080
	global_load_lds_dwordx4 v[2:3], off
	v_lshl_add_u64 v[2:3], v[4:5], 0, s[10:11]
	s_mov_b32 m0, s58
	s_addc_u32 s21, s45, 0
	global_load_lds_dwordx4 v[2:3], off
	s_add_i32 m0, s43, 0x1c000
	v_lshl_add_u64 v[2:3], s[20:21], 0, v[140:141]
	global_load_lds_dwordx4 v[2:3], off
	v_lshl_add_u64 v[2:3], s[20:21], 0, v[144:145]
	s_add_i32 m0, s43, 0x1e000
	s_cmpk_lt_u32 s12, 0x100
	global_load_lds_dwordx4 v[2:3], off
	v_lshrrev_b32_e32 v3, 1, v10
	v_and_b32_e32 v3, 24, v3
	v_and_b32_e32 v2, 15, v10
	v_lshlrev_b32_e32 v4, 1, v3
	v_lshl_or_b32 v170, s18, 6, v2
	v_lshl_or_b32 v4, v2, 6, v4
	v_lshlrev_b32_e32 v2, 2, v2
	v_and_b32_e32 v5, 32, v2
	v_bitop3_b32 v6, v4, s13, v5 bitop3:0xde
	s_cselect_b64 s[12:13], -1, 0
	s_lshl_b32 s18, s18, 8
	s_add_i32 s18, s18, 0
	s_add_i32 s18, s18, 0x20400
	v_add_u32_e32 v175, s18, v2
	v_lshlrev_b32_e32 v2, 14, v11
	v_and_b32_e32 v2, 0xffff8000, v2
	v_or_b32_e32 v173, s19, v3
	v_lshl_add_u32 v2, v12, 11, v2
	v_and_b32_e32 v3, 1, v11
	v_lshl_or_b32 v2, v3, 6, v2
	v_lshl_add_u32 v146, v13, 1, v2
	v_lshlrev_b32_e32 v2, 14, v14
	v_and_b32_e32 v2, 0xffff8000, v2
	v_lshl_add_u32 v2, v15, 11, v2
	v_and_b32_e32 v3, 1, v14
	s_mov_b64 s[20:21], 0x40080
	s_waitcnt vmcnt(0)
	v_readlane_b32 s18, v245, 0
	v_lshl_or_b32 v2, v3, 6, v2
	s_bitcmp1_b32 s18, 0
	v_lshl_add_u64 v[148:149], v[146:147], 0, s[20:21]
	v_lshl_add_u32 v146, v16, 1, v2
	s_mov_b32 s59, 0
	v_bitop3_b32 v171, v4, s22, v5 bitop3:0xde
	v_add_u32_e32 v240, 0x10000, v171
	v_and_b32_e32 v172, 63, v0
	v_or_b32_e32 v174, 0xfffffc00, v173
	s_cselect_b64 s[18:19], -1, 0
	v_lshl_add_u64 v[150:151], v[146:147], 0, s[20:21]
	s_add_i32 s60, 0, 0x10000
	s_add_i32 s61, 0, 0x14000
	v_add_u32_e32 v176, 0, v6
	s_mov_b64 s[20:21], 0x20000
	s_mov_b64 s[22:23], 0x24000
	s_mov_b64 s[24:25], 0x28000
	s_mov_b64 s[26:27], 0x2c000
	v_mov_b64_e32 v[152:153], 0x40000
	v_mov_b64_e32 v[154:155], 0x48000
	v_mov_b64_e32 v[156:157], 0x50000
	v_mov_b64_e32 v[158:159], 0x58000
	v_mov_b32_e32 v177, 0x3e38aa3b
	s_barrier
	s_branch .LBB0_175

.LBB0_177:
	s_ashr_i32 s29, s28, 31
	s_lshl_b64 s[38:39], s[28:29], 19
	s_add_u32 s38, s84, s38
	s_addc_u32 s39, s85, s39
	s_and_b64 s[40:41], s[36:37], exec
	s_cselect_b32 s29, s39, s1
	s_cselect_b32 s62, s38, s0
	s_ashr_i32 s35, s34, 31
	s_lshl_b64 s[40:41], s[34:35], 19
	s_add_u32 s40, s16, s40
	s_addc_u32 s41, s17, s41
	s_and_b64 s[46:47], s[36:37], exec
	s_cselect_b32 s63, s41, s45
	s_cselect_b32 s64, s40, s44
	s_lshl_b32 s35, s30, 8
	s_add_u32 s65, s44, 0x100
	v_mov_b32_e32 v2, 0
	v_or_b32_e32 v134, s35, v172
	v_lshl_add_u64 v[130:131], s[0:1], 0, v[148:149]
	v_lshl_add_u64 v[132:133], s[0:1], 0, v[150:151]
	s_addc_u32 s66, s45, 0
	s_mov_b32 s67, -2
	s_mov_b64 s[30:31], 0
	s_waitcnt lgkmcnt(0)
	ds_read_b128 v[160:163], v240
	ds_read_b128 v[164:167], v240 offset:1024
	ds_read_b128 v[178:181], v240 offset:2048
	ds_read_b128 v[182:185], v240 offset:3072
	s_add_u32 s44, s0, s30
	ds_read_b128 v[186:189], v240 offset:16384
	ds_read_b128 v[190:193], v240 offset:17408
	ds_read_b128 v[194:197], v240 offset:18432
	ds_read_b128 v[198:201], v240 offset:19456
	s_addc_u32 s45, s1, s31
	s_add_u32 s44, s44, 0x100
	s_addc_u32 s45, s45, 0
	s_add_u32 s72, s65, s30
	s_addc_u32 s73, s66, s31
	s_cmpk_eq_i32 s30, 0x700
	s_cselect_b32 s47, s29, s45
	s_cselect_b32 s46, s62, s44
	s_cselect_b32 s45, s63, s73
	s_cselect_b32 s44, s64, s72
	s_add_u32 s90, s0, s30
	s_addc_u32 s91, s1, s31
	s_add_i32 m0, s43, 0xc000
	ds_read_b128 v[202:205], v176
	ds_read_b128 v[206:209], v176 offset:1024
	ds_read_b128 v[210:213], v176 offset:2048
	ds_read_b128 v[214:217], v176 offset:3072
	ds_read_b128 v[218:221], v176 offset:4096
	ds_read_b128 v[222:225], v176 offset:5120
	ds_read_b128 v[226:229], v176 offset:6144
	ds_read_b128 v[230:233], v176 offset:7168
	global_load_lds_dwordx4 v148, s[90:91]
	s_add_i32 m0, s43, 0xe000
	s_nop 0
	global_load_lds_dwordx4 v150, s[90:91]
	s_nop 0
	s_waitcnt lgkmcnt(0)
	s_barrier
	s_setprio 1
	v_mfma_f32_16x16x32_bf16 v[126:129], v[160:163], v[202:205], 0
	v_mfma_f32_16x16x32_bf16 v[122:125], v[178:181], v[202:205], 0
	v_mfma_f32_16x16x32_bf16 v[110:113], v[160:163], v[210:213], 0
	v_mfma_f32_16x16x32_bf16 v[106:109], v[178:181], v[210:213], 0
	v_mfma_f32_16x16x32_bf16 v[94:97], v[160:163], v[218:221], 0
	v_mfma_f32_16x16x32_bf16 v[90:93], v[178:181], v[218:221], 0
	v_mfma_f32_16x16x32_bf16 v[78:81], v[160:163], v[226:229], 0
	v_mfma_f32_16x16x32_bf16 v[74:77], v[178:181], v[226:229], 0
	v_mfma_f32_16x16x32_bf16 v[126:129], v[164:167], v[206:209], v[126:129]
	v_mfma_f32_16x16x32_bf16 v[122:125], v[182:185], v[206:209], v[122:125]
	v_mfma_f32_16x16x32_bf16 v[110:113], v[164:167], v[214:217], v[110:113]
	v_mfma_f32_16x16x32_bf16 v[106:109], v[182:185], v[214:217], v[106:109]
	v_mfma_f32_16x16x32_bf16 v[94:97], v[164:167], v[222:225], v[94:97]
	v_mfma_f32_16x16x32_bf16 v[90:93], v[182:185], v[222:225], v[90:93]
	v_mfma_f32_16x16x32_bf16 v[78:81], v[164:167], v[230:233], v[78:81]
	v_mfma_f32_16x16x32_bf16 v[74:77], v[182:185], v[230:233], v[74:77]
	v_mfma_f32_16x16x32_bf16 v[118:121], v[186:189], v[202:205], 0
	v_mfma_f32_16x16x32_bf16 v[114:117], v[194:197], v[202:205], 0
	v_mfma_f32_16x16x32_bf16 v[102:105], v[186:189], v[210:213], 0
	v_mfma_f32_16x16x32_bf16 v[98:101], v[194:197], v[210:213], 0
	v_mfma_f32_16x16x32_bf16 v[86:89], v[186:189], v[218:221], 0
	v_mfma_f32_16x16x32_bf16 v[82:85], v[194:197], v[218:221], 0
	v_mfma_f32_16x16x32_bf16 v[70:73], v[186:189], v[226:229], 0
	v_mfma_f32_16x16x32_bf16 v[66:69], v[194:197], v[226:229], 0
	v_mfma_f32_16x16x32_bf16 v[118:121], v[190:193], v[206:209], v[118:121]
	v_mfma_f32_16x16x32_bf16 v[114:117], v[198:201], v[206:209], v[114:117]
	v_mfma_f32_16x16x32_bf16 v[102:105], v[190:193], v[214:217], v[102:105]
	v_mfma_f32_16x16x32_bf16 v[98:101], v[198:201], v[214:217], v[98:101]
	s_setprio 2
	s_barrier
	v_mfma_f32_16x16x32_bf16 v[86:89], v[190:193], v[222:225], v[86:89]
	v_mfma_f32_16x16x32_bf16 v[82:85], v[198:201], v[222:225], v[82:85]
	v_mfma_f32_16x16x32_bf16 v[70:73], v[190:193], v[230:233], v[70:73]
	v_mfma_f32_16x16x32_bf16 v[66:69], v[198:201], v[230:233], v[66:69]
	s_setprio 0
	s_nop 0
	s_add_i32 s72, s60, s33
	s_mov_b32 m0, s72
	ds_read_b128 v[202:205], v176 offset:16384
	ds_read_b128 v[206:209], v176 offset:17408
	ds_read_b128 v[210:213], v176 offset:18432
	ds_read_b128 v[214:217], v176 offset:19456
	ds_read_b128 v[218:221], v176 offset:20480
	ds_read_b128 v[222:225], v176 offset:21504
	ds_read_b128 v[226:229], v176 offset:22528
	ds_read_b128 v[230:233], v176 offset:23552
	global_load_lds_dwordx4 v140, s[44:45]
	s_add_i32 m0, s72, 0x2000
	s_add_u32 s72, s44, 0x40000
	s_addc_u32 s73, s45, 0
	s_add_i32 s74, s61, s33
	global_load_lds_dwordx4 v144, s[44:45]
	s_mov_b32 m0, s74
	s_add_u32 s94, s46, 0x80
	s_addc_u32 s95, s47, 0
	global_load_lds_dwordx4 v140, s[72:73]
	s_add_i32 m0, s74, 0x2000
	s_nop 0
	global_load_lds_dwordx4 v144, s[72:73]
	s_mov_b32 m0, s43
	s_nop 0
	global_load_lds_dwordx4 v138, s[46:47]
	s_mov_b32 m0, s54
	s_nop 0
	global_load_lds_dwordx4 v142, s[46:47]
	s_nop 0
	s_waitcnt lgkmcnt(0)
	s_barrier
	s_setprio 1
	v_mfma_f32_16x16x32_bf16 v[62:65], v[160:163], v[202:205], 0
	v_mfma_f32_16x16x32_bf16 v[58:61], v[178:181], v[202:205], 0
	v_mfma_f32_16x16x32_bf16 v[46:49], v[160:163], v[210:213], 0
	v_mfma_f32_16x16x32_bf16 v[42:45], v[178:181], v[210:213], 0
	v_mfma_f32_16x16x32_bf16 v[30:33], v[160:163], v[218:221], 0
	v_mfma_f32_16x16x32_bf16 v[26:29], v[178:181], v[218:221], 0
	v_mfma_f32_16x16x32_bf16 v[14:17], v[160:163], v[226:229], 0
	v_mfma_f32_16x16x32_bf16 v[10:13], v[178:181], v[226:229], 0
	v_mfma_f32_16x16x32_bf16 v[62:65], v[164:167], v[206:209], v[62:65]
	v_mfma_f32_16x16x32_bf16 v[58:61], v[182:185], v[206:209], v[58:61]
	v_mfma_f32_16x16x32_bf16 v[46:49], v[164:167], v[214:217], v[46:49]
	v_mfma_f32_16x16x32_bf16 v[42:45], v[182:185], v[214:217], v[42:45]
	v_mfma_f32_16x16x32_bf16 v[30:33], v[164:167], v[222:225], v[30:33]
	v_mfma_f32_16x16x32_bf16 v[26:29], v[182:185], v[222:225], v[26:29]
	v_mfma_f32_16x16x32_bf16 v[14:17], v[164:167], v[230:233], v[14:17]
	v_mfma_f32_16x16x32_bf16 v[10:13], v[182:185], v[230:233], v[10:13]
	v_mfma_f32_16x16x32_bf16 v[54:57], v[186:189], v[202:205], 0
	v_mfma_f32_16x16x32_bf16 v[50:53], v[194:197], v[202:205], 0
	v_mfma_f32_16x16x32_bf16 v[38:41], v[186:189], v[210:213], 0
	v_mfma_f32_16x16x32_bf16 v[34:37], v[194:197], v[210:213], 0
	v_mfma_f32_16x16x32_bf16 v[22:25], v[186:189], v[218:221], 0
	v_mfma_f32_16x16x32_bf16 v[18:21], v[194:197], v[218:221], 0
	v_mfma_f32_16x16x32_bf16 v[6:9], v[186:189], v[226:229], 0
	v_mfma_f32_16x16x32_bf16 v[2:5], v[194:197], v[226:229], 0
	v_mfma_f32_16x16x32_bf16 v[54:57], v[190:193], v[206:209], v[54:57]
	v_mfma_f32_16x16x32_bf16 v[50:53], v[198:201], v[206:209], v[50:53]
	v_mfma_f32_16x16x32_bf16 v[38:41], v[190:193], v[214:217], v[38:41]
	v_mfma_f32_16x16x32_bf16 v[34:37], v[198:201], v[214:217], v[34:37]
	s_setprio 2
	s_barrier
	v_mfma_f32_16x16x32_bf16 v[22:25], v[190:193], v[222:225], v[22:25]
	v_mfma_f32_16x16x32_bf16 v[18:21], v[198:201], v[222:225], v[18:21]
	v_mfma_f32_16x16x32_bf16 v[6:9], v[190:193], v[230:233], v[6:9]
	v_mfma_f32_16x16x32_bf16 v[2:5], v[198:201], v[230:233], v[2:5]
	s_setprio 0
	s_nop 0
	s_add_i32 s72, 0, 0x18000
	s_add_i32 s73, 0, 0x1c000
	ds_read_b128 v[160:163], v240 offset:32768
	ds_read_b128 v[164:167], v240 offset:33792
	ds_read_b128 v[178:181], v240 offset:34816
	ds_read_b128 v[182:185], v240 offset:35840
	ds_read_b128 v[186:189], v240 offset:49152
	ds_read_b128 v[190:193], v240 offset:50176
	ds_read_b128 v[194:197], v240 offset:51200
	ds_read_b128 v[198:201], v240 offset:52224
	s_add_u32 s46, s46, 0x40000
	s_addc_u32 s47, s47, 0
	s_mov_b32 m0, s55
	ds_read_b128 v[202:205], v176 offset:32768
	ds_read_b128 v[206:209], v176 offset:33792
	ds_read_b128 v[210:213], v176 offset:34816
	ds_read_b128 v[214:217], v176 offset:35840
	ds_read_b128 v[218:221], v176 offset:36864
	ds_read_b128 v[222:225], v176 offset:37888
	ds_read_b128 v[226:229], v176 offset:38912
	ds_read_b128 v[230:233], v176 offset:39936
	global_load_lds_dwordx4 v138, s[46:47]
	s_mov_b32 m0, s56
	s_nop 0
	global_load_lds_dwordx4 v142, s[46:47]
	s_waitcnt vmcnt(8)
	s_waitcnt lgkmcnt(0)
	s_barrier
	s_setprio 1
	v_mfma_f32_16x16x32_bf16 v[126:129], v[160:163], v[202:205], v[126:129]
	v_mfma_f32_16x16x32_bf16 v[122:125], v[178:181], v[202:205], v[122:125]
	v_mfma_f32_16x16x32_bf16 v[110:113], v[160:163], v[210:213], v[110:113]
	v_mfma_f32_16x16x32_bf16 v[106:109], v[178:181], v[210:213], v[106:109]
	v_mfma_f32_16x16x32_bf16 v[94:97], v[160:163], v[218:221], v[94:97]
	v_mfma_f32_16x16x32_bf16 v[90:93], v[178:181], v[218:221], v[90:93]
	v_mfma_f32_16x16x32_bf16 v[78:81], v[160:163], v[226:229], v[78:81]
	v_mfma_f32_16x16x32_bf16 v[74:77], v[178:181], v[226:229], v[74:77]
	v_mfma_f32_16x16x32_bf16 v[126:129], v[164:167], v[206:209], v[126:129]
	v_mfma_f32_16x16x32_bf16 v[122:125], v[182:185], v[206:209], v[122:125]
	v_mfma_f32_16x16x32_bf16 v[110:113], v[164:167], v[214:217], v[110:113]
	v_mfma_f32_16x16x32_bf16 v[106:109], v[182:185], v[214:217], v[106:109]
	v_mfma_f32_16x16x32_bf16 v[94:97], v[164:167], v[222:225], v[94:97]
	v_mfma_f32_16x16x32_bf16 v[90:93], v[182:185], v[222:225], v[90:93]
	v_mfma_f32_16x16x32_bf16 v[78:81], v[164:167], v[230:233], v[78:81]
	v_mfma_f32_16x16x32_bf16 v[74:77], v[182:185], v[230:233], v[74:77]
	v_mfma_f32_16x16x32_bf16 v[118:121], v[186:189], v[202:205], v[118:121]
	v_mfma_f32_16x16x32_bf16 v[114:117], v[194:197], v[202:205], v[114:117]
	v_mfma_f32_16x16x32_bf16 v[102:105], v[186:189], v[210:213], v[102:105]
	v_mfma_f32_16x16x32_bf16 v[98:101], v[194:197], v[210:213], v[98:101]
	v_mfma_f32_16x16x32_bf16 v[86:89], v[186:189], v[218:221], v[86:89]
	v_mfma_f32_16x16x32_bf16 v[82:85], v[194:197], v[218:221], v[82:85]
	v_mfma_f32_16x16x32_bf16 v[70:73], v[186:189], v[226:229], v[70:73]
	v_mfma_f32_16x16x32_bf16 v[66:69], v[194:197], v[226:229], v[66:69]
	v_mfma_f32_16x16x32_bf16 v[118:121], v[190:193], v[206:209], v[118:121]
	v_mfma_f32_16x16x32_bf16 v[114:117], v[198:201], v[206:209], v[114:117]
	v_mfma_f32_16x16x32_bf16 v[102:105], v[190:193], v[214:217], v[102:105]
	v_mfma_f32_16x16x32_bf16 v[98:101], v[198:201], v[214:217], v[98:101]
	s_setprio 2
	s_barrier
	v_mfma_f32_16x16x32_bf16 v[86:89], v[190:193], v[222:225], v[86:89]
	v_mfma_f32_16x16x32_bf16 v[82:85], v[198:201], v[222:225], v[82:85]
	v_mfma_f32_16x16x32_bf16 v[70:73], v[190:193], v[230:233], v[70:73]
	v_mfma_f32_16x16x32_bf16 v[66:69], v[198:201], v[230:233], v[66:69]
	s_setprio 0
	s_nop 0
	s_add_i32 s46, s72, s33
	s_add_u32 s96, s44, 0x80
	s_addc_u32 s97, s45, 0
	s_mov_b32 m0, s46
	ds_read_b128 v[202:205], v176 offset:49152
	ds_read_b128 v[206:209], v176 offset:50176
	ds_read_b128 v[210:213], v176 offset:51200
	ds_read_b128 v[214:217], v176 offset:52224
	ds_read_b128 v[218:221], v176 offset:53248
	ds_read_b128 v[222:225], v176 offset:54272
	ds_read_b128 v[226:229], v176 offset:55296
	ds_read_b128 v[230:233], v176 offset:56320
	global_load_lds_dwordx4 v140, s[96:97]
	s_add_i32 m0, s46, 0x2000
	s_add_u32 s44, s44, 0x40080
	s_addc_u32 s45, s45, 0
	s_add_i32 s46, s73, s33
	global_load_lds_dwordx4 v144, s[96:97]
	s_mov_b32 m0, s46
	s_nop 0
	global_load_lds_dwordx4 v140, s[44:45]
	s_add_i32 m0, s46, 0x2000
	s_nop 0
	global_load_lds_dwordx4 v144, s[44:45]
	s_mov_b32 m0, s57
	s_nop 0
	global_load_lds_dwordx4 v138, s[94:95]
	s_mov_b32 m0, s58
	s_nop 0
	global_load_lds_dwordx4 v142, s[94:95]
	s_waitcnt vmcnt(8)
	s_waitcnt lgkmcnt(0)
	s_barrier
	s_setprio 1
	v_mfma_f32_16x16x32_bf16 v[62:65], v[160:163], v[202:205], v[62:65]
	v_mfma_f32_16x16x32_bf16 v[58:61], v[178:181], v[202:205], v[58:61]
	v_mfma_f32_16x16x32_bf16 v[46:49], v[160:163], v[210:213], v[46:49]
	v_mfma_f32_16x16x32_bf16 v[42:45], v[178:181], v[210:213], v[42:45]
	v_mfma_f32_16x16x32_bf16 v[30:33], v[160:163], v[218:221], v[30:33]
	v_mfma_f32_16x16x32_bf16 v[26:29], v[178:181], v[218:221], v[26:29]
	v_mfma_f32_16x16x32_bf16 v[14:17], v[160:163], v[226:229], v[14:17]
	v_mfma_f32_16x16x32_bf16 v[10:13], v[178:181], v[226:229], v[10:13]
	v_mfma_f32_16x16x32_bf16 v[62:65], v[164:167], v[206:209], v[62:65]
	v_mfma_f32_16x16x32_bf16 v[58:61], v[182:185], v[206:209], v[58:61]
	v_mfma_f32_16x16x32_bf16 v[46:49], v[164:167], v[214:217], v[46:49]
	v_mfma_f32_16x16x32_bf16 v[42:45], v[182:185], v[214:217], v[42:45]
	v_mfma_f32_16x16x32_bf16 v[30:33], v[164:167], v[222:225], v[30:33]
	v_mfma_f32_16x16x32_bf16 v[26:29], v[182:185], v[222:225], v[26:29]
	v_mfma_f32_16x16x32_bf16 v[14:17], v[164:167], v[230:233], v[14:17]
	v_mfma_f32_16x16x32_bf16 v[10:13], v[182:185], v[230:233], v[10:13]
	v_mfma_f32_16x16x32_bf16 v[54:57], v[186:189], v[202:205], v[54:57]
	v_mfma_f32_16x16x32_bf16 v[50:53], v[194:197], v[202:205], v[50:53]
	v_mfma_f32_16x16x32_bf16 v[38:41], v[186:189], v[210:213], v[38:41]
	v_mfma_f32_16x16x32_bf16 v[34:37], v[194:197], v[210:213], v[34:37]
	v_mfma_f32_16x16x32_bf16 v[22:25], v[186:189], v[218:221], v[22:25]
	v_mfma_f32_16x16x32_bf16 v[18:21], v[194:197], v[218:221], v[18:21]
	v_mfma_f32_16x16x32_bf16 v[6:9], v[186:189], v[226:229], v[6:9]
	v_mfma_f32_16x16x32_bf16 v[2:5], v[194:197], v[226:229], v[2:5]
	v_mfma_f32_16x16x32_bf16 v[54:57], v[190:193], v[206:209], v[54:57]
	v_mfma_f32_16x16x32_bf16 v[50:53], v[198:201], v[206:209], v[50:53]
	v_mfma_f32_16x16x32_bf16 v[38:41], v[190:193], v[214:217], v[38:41]
	v_mfma_f32_16x16x32_bf16 v[34:37], v[198:201], v[214:217], v[34:37]
	s_setprio 2
	s_barrier
	v_mfma_f32_16x16x32_bf16 v[22:25], v[190:193], v[222:225], v[22:25]
	v_mfma_f32_16x16x32_bf16 v[18:21], v[198:201], v[222:225], v[18:21]
	v_mfma_f32_16x16x32_bf16 v[6:9], v[190:193], v[230:233], v[6:9]
	v_mfma_f32_16x16x32_bf16 v[2:5], v[198:201], v[230:233], v[2:5]
	s_setprio 0
	s_nop 0
	s_add_i32 s67, s67, 2
	s_add_u32 s30, s30, 0x100
	s_addc_u32 s31, s31, 0
	s_cmp_gt_u32 s67, 13
	s_cbranch_scc1 .LBB0_181
	s_branch .LBB0_179

.LBB0_183:
	s_waitcnt vmcnt(0)
	ds_read2_b32 v[168:169], v175 offset1:16
	ds_read2_b32 v[166:167], v175 offset0:32 offset1:48
	ds_read2_b32 v[164:165], v175 offset0:128 offset1:144
	ds_read2_b32 v[162:163], v175 offset0:160 offset1:176
	v_add_u32_e32 v160, s35, v170
	s_cmp_gt_i32 s42, 7
	s_mov_b64 s[0:1], -1
	s_cbranch_scc0 .LBB0_217
	s_waitcnt lgkmcnt(0)
	v_mul_f32_e32 v130, 0xbfb8aa3b, v168
	v_mul_f32_e32 v131, v126, v130
	v_exp_f32_e32 v131, v131
	v_mul_f32_e32 v132, v118, v130
	v_exp_f32_e32 v132, v132
	v_mul_f32_e32 v133, v127, v130
	v_add_f32_e32 v131, 1.0, v131
	v_mul_f32_e32 v134, v119, v130
	v_rcp_f32_e32 v131, v131
	v_exp_f32_e32 v133, v133
	v_exp_f32_e32 v134, v134
	v_add_f32_e32 v132, 1.0, v132
	v_min_f32_e32 v132, 0x7149f2ca, v132
	v_rcp_f32_e32 v135, v132
	v_mul_f32_e32 v131, v131, v132
	v_add_f32_e32 v132, 1.0, v133
	v_add_f32_e32 v133, 1.0, v134
	v_mul_f32_e32 v134, v128, v130
	v_mul_f32_e32 v136, v120, v130
	v_rcp_f32_e32 v132, v132
	v_exp_f32_e32 v134, v134
	v_exp_f32_e32 v136, v136
	v_min_f32_e32 v133, 0x7149f2ca, v133
	v_rcp_f32_e32 v137, v133
	v_mul_f32_e32 v132, v132, v133
	v_add_f32_e32 v133, 1.0, v134
	v_add_f32_e32 v134, 1.0, v136
	v_mul_f32_e32 v136, v129, v130
	v_mul_f32_e32 v146, v121, v130
	v_rcp_f32_e32 v133, v133
	v_exp_f32_e32 v136, v136
	v_exp_f32_e32 v146, v146
	v_min_f32_e32 v134, 0x7149f2ca, v134
	v_rcp_f32_e32 v161, v134
	v_mul_f32_e32 v133, v133, v134
	v_add_f32_e32 v134, 1.0, v136
	v_add_f32_e32 v136, 1.0, v146
	v_mul_f32_e32 v146, v122, v130
	v_mul_f32_e32 v178, v114, v130
	v_rcp_f32_e32 v134, v134
	v_exp_f32_e32 v146, v146
	v_exp_f32_e32 v178, v178
	v_min_f32_e32 v136, 0x7149f2ca, v136
	v_rcp_f32_e32 v179, v136
	v_mul_f32_e32 v134, v134, v136
	v_add_f32_e32 v136, 1.0, v146
	v_add_f32_e32 v146, 1.0, v178
	v_mul_f32_e32 v178, v123, v130
	v_mul_f32_e32 v180, v115, v130
	v_rcp_f32_e32 v136, v136
	v_exp_f32_e32 v178, v178
	v_exp_f32_e32 v180, v180
	v_min_f32_e32 v146, 0x7149f2ca, v146
	v_rcp_f32_e32 v181, v146
	v_mul_f32_e32 v136, v136, v146
	v_add_f32_e32 v146, 1.0, v178
	v_add_f32_e32 v178, 1.0, v180
	v_mul_f32_e32 v180, v124, v130
	v_rcp_f32_e32 v146, v146
	v_exp_f32_e32 v180, v180
	v_mul_f32_e32 v182, v116, v130
	v_min_f32_e32 v178, 0x7149f2ca, v178
	v_exp_f32_e32 v182, v182
	v_rcp_f32_e32 v183, v178
	v_mul_f32_e32 v146, v146, v178
	v_add_f32_e32 v178, 1.0, v180
	v_mul_f32_e32 v184, v125, v130
	v_rcp_f32_e32 v178, v178
	v_exp_f32_e32 v184, v184
	v_add_f32_e32 v180, 1.0, v182
	v_mul_f32_e32 v130, v117, v130
	v_min_f32_e32 v180, 0x7149f2ca, v180
	v_exp_f32_e32 v130, v130
	v_rcp_f32_e32 v182, v180
	v_mul_f32_e32 v178, v178, v180
	v_add_f32_e32 v180, 1.0, v184
	v_rcp_f32_e32 v180, v180
	v_add_f32_e32 v130, 1.0, v130
	v_min_f32_e32 v130, 0x7149f2ca, v130
	s_and_b64 vcc, exec, s[18:19]
	v_rcp_f32_e32 v184, v130
	v_mul_f32_e32 v180, v180, v130
	v_cvt_pk_bf16_f32 v130, v131, v132
	v_cvt_pk_bf16_f32 v131, v133, v134
	v_cvt_pk_bf16_f32 v132, v136, v146
	v_cvt_pk_bf16_f32 v133, v178, v180
	v_cvt_pk_bf16_f32 v134, v135, v137
	v_cvt_pk_bf16_f32 v135, v161, v179
	v_cvt_pk_bf16_f32 v136, v181, v183
	v_cvt_pk_bf16_f32 v137, v182, v184
	s_cbranch_vccz .LBB0_186
	s_mov_b64 s[0:1], 0

.LBB0_939:
	s_lshl_b32 s2, s2, 5
	s_and_b32 s12, s2, 0x60
	s_mov_b64 s[2:3], 0x80
	s_add_i32 m0, s27, 0x18000
	v_lshl_add_u64 v[8:9], v[8:9], 0, s[2:3]
	s_lshl_b32 s9, s8, 13
	s_lshl_b32 s13, s12, 7
	s_waitcnt vmcnt(2)
	s_barrier
	global_load_lds_dwordx4 v[8:9], off
	v_lshl_add_u64 v[6:7], v[6:7], 0, s[2:3]
	s_add_i32 m0, s27, 0x1a000
	s_add_i32 s33, s27, 0x8000
	s_add_i32 s34, s27, 0xa000
	global_load_lds_dwordx4 v[6:7], off
	v_lshl_add_u64 v[2:3], v[2:3], 0, s[2:3]
	s_mov_b32 m0, s33
	s_add_u32 s10, s22, 0x40080
	global_load_lds_dwordx4 v[2:3], off
	v_lshl_add_u64 v[2:3], v[4:5], 0, s[2:3]
	s_mov_b32 m0, s34
	s_addc_u32 s11, s23, 0
	global_load_lds_dwordx4 v[2:3], off
	s_add_i32 m0, s27, 0x1c000
	v_lshl_add_u64 v[2:3], s[10:11], 0, v[134:135]
	global_load_lds_dwordx4 v[2:3], off
	v_lshl_add_u64 v[2:3], s[10:11], 0, v[130:131]
	s_add_i32 m0, s27, 0x1e000
	s_cmpk_lt_u32 s7, 0x100
	global_load_lds_dwordx4 v[2:3], off
	v_and_b32_e32 v2, 15, v12
	v_lshrrev_b32_e32 v3, 1, v12
	s_sext_i32_i16 s38, s6
	v_lshl_or_b32 v148, s8, 6, v2
	v_and_b32_e32 v3, 24, v3
	s_cselect_b64 s[6:7], -1, 0
	s_lshl_b32 s8, s8, 8
	v_lshlrev_b32_e32 v4, 1, v3
	s_add_i32 s8, s8, 0
	v_lshl_or_b32 v4, v2, 6, v4
	v_lshlrev_b32_e32 v2, 2, v2
	s_add_i32 s8, s8, 0x20400
	v_and_b32_e32 v5, 32, v2
	v_add_u32_e32 v150, s8, v2
	v_lshlrev_b32_e32 v2, 14, v15
	v_and_b32_e32 v2, 0xffff8000, v2
	v_or_b32_e32 v151, s12, v3
	v_lshl_add_u32 v2, v14, 11, v2
	v_and_b32_e32 v3, 1, v15
	v_lshl_or_b32 v2, v3, 6, v2
	s_mov_b64 s[10:11], 0x40080
	v_lshl_add_u32 v2, v16, 1, v2
	v_mov_b32_e32 v3, v135
	v_lshl_add_u64 v[138:139], v[2:3], 0, s[10:11]
	v_lshlrev_b32_e32 v2, 14, v10
	v_and_b32_e32 v2, 0xffff8000, v2
	v_lshl_add_u32 v2, v11, 11, v2
	v_and_b32_e32 v3, 1, v10
	s_waitcnt vmcnt(0)
	v_lshl_or_b32 v2, v3, 6, v2
	v_bitop3_b32 v6, v4, s9, v5 bitop3:0xde
	v_lshl_add_u32 v2, v13, 1, v2
	v_mov_b32_e32 v3, v135
	v_bitop3_b32 v149, v4, s13, v5 bitop3:0xde
	v_add_u32_e32 v229, 0x10000, v149
	v_lshl_add_u64 v[140:141], v[2:3], 0, s[10:11]
	s_add_i32 s35, 0, 0x10000
	s_add_i32 s36, 0, 0x14000
	v_add_u32_e32 v152, 0, v6
	v_mov_b32_e32 v153, 0x358637bd
	s_movk_i32 s37, 0x1600
	s_barrier
	s_branch .LBB0_942

.LBB0_944:
	s_ashr_i32 s9, s8, 31
	s_lshl_b64 s[14:15], s[8:9], 19
	s_add_u32 s14, s64, s14
	s_addc_u32 s15, s65, s15
	s_and_b64 s[16:17], s[12:13], exec
	s_cselect_b32 s9, s15, s19
	s_cselect_b32 s39, s14, s18
	s_ashr_i32 s11, s10, 31
	s_lshl_b64 s[16:17], s[10:11], 19
	v_readlane_b32 s24, v245, 3
	v_readlane_b32 s25, v245, 4
	s_add_u32 s16, s24, s16
	s_addc_u32 s17, s25, s17
	s_and_b64 s[24:25], s[12:13], exec
	s_cselect_b32 s40, s17, s23
	s_cselect_b32 s41, s16, s22
	s_lshl_b32 s11, s20, 8
	s_add_u32 s42, s22, 0x100
	v_mov_b32_e32 v2, 0
	v_or_b32_e32 v146, s11, v228
	v_lshl_add_u64 v[142:143], s[18:19], 0, v[138:139]
	v_lshl_add_u64 v[144:145], s[18:19], 0, v[140:141]
	s_addc_u32 s43, s23, 0
	s_mov_b32 s44, -2
	s_mov_b64 s[20:21], 0
	ds_read_b128 v[154:157], v229
	ds_read_b128 v[158:161], v229 offset:1024
	ds_read_b128 v[162:165], v229 offset:2048
	ds_read_b128 v[166:169], v229 offset:3072
	s_add_u32 s22, s18, s20
	ds_read_b128 v[170:173], v229 offset:16384
	ds_read_b128 v[174:177], v229 offset:17408
	ds_read_b128 v[178:181], v229 offset:18432
	ds_read_b128 v[182:185], v229 offset:19456
	s_addc_u32 s23, s19, s21
	s_add_u32 s22, s22, 0x100
	s_addc_u32 s23, s23, 0
	s_add_u32 s45, s42, s20
	s_addc_u32 s46, s43, s21
	s_cmpk_eq_i32 s20, 0x700
	s_cselect_b32 s25, s9, s23
	s_cselect_b32 s24, s39, s22
	s_cselect_b32 s23, s40, s46
	s_cselect_b32 s22, s41, s45
	s_add_u32 s48, s18, s20
	s_addc_u32 s49, s19, s21
	s_add_i32 m0, s27, 0xc000
	ds_read_b128 v[186:189], v152
	ds_read_b128 v[190:193], v152 offset:1024
	ds_read_b128 v[194:197], v152 offset:2048
	ds_read_b128 v[198:201], v152 offset:3072
	ds_read_b128 v[202:205], v152 offset:4096
	ds_read_b128 v[206:209], v152 offset:5120
	ds_read_b128 v[210:213], v152 offset:6144
	ds_read_b128 v[214:217], v152 offset:7168
	global_load_lds_dwordx4 v138, s[48:49]
	s_add_i32 m0, s27, 0xe000
	s_nop 0
	global_load_lds_dwordx4 v140, s[48:49]
	s_nop 0
	s_waitcnt lgkmcnt(0)
	s_barrier
	s_setprio 1
	v_mfma_f32_16x16x32_bf16 v[126:129], v[154:157], v[186:189], 0
	v_mfma_f32_16x16x32_bf16 v[118:121], v[162:165], v[186:189], 0
	v_mfma_f32_16x16x32_bf16 v[110:113], v[154:157], v[194:197], 0
	v_mfma_f32_16x16x32_bf16 v[102:105], v[162:165], v[194:197], 0
	v_mfma_f32_16x16x32_bf16 v[94:97], v[154:157], v[202:205], 0
	v_mfma_f32_16x16x32_bf16 v[86:89], v[162:165], v[202:205], 0
	v_mfma_f32_16x16x32_bf16 v[78:81], v[154:157], v[210:213], 0
	v_mfma_f32_16x16x32_bf16 v[70:73], v[162:165], v[210:213], 0
	v_mfma_f32_16x16x32_bf16 v[126:129], v[158:161], v[190:193], v[126:129]
	v_mfma_f32_16x16x32_bf16 v[118:121], v[166:169], v[190:193], v[118:121]
	v_mfma_f32_16x16x32_bf16 v[110:113], v[158:161], v[198:201], v[110:113]
	v_mfma_f32_16x16x32_bf16 v[102:105], v[166:169], v[198:201], v[102:105]
	v_mfma_f32_16x16x32_bf16 v[94:97], v[158:161], v[206:209], v[94:97]
	v_mfma_f32_16x16x32_bf16 v[86:89], v[166:169], v[206:209], v[86:89]
	v_mfma_f32_16x16x32_bf16 v[78:81], v[158:161], v[214:217], v[78:81]
	v_mfma_f32_16x16x32_bf16 v[70:73], v[166:169], v[214:217], v[70:73]
	v_mfma_f32_16x16x32_bf16 v[122:125], v[170:173], v[186:189], 0
	v_mfma_f32_16x16x32_bf16 v[114:117], v[178:181], v[186:189], 0
	v_mfma_f32_16x16x32_bf16 v[106:109], v[170:173], v[194:197], 0
	v_mfma_f32_16x16x32_bf16 v[98:101], v[178:181], v[194:197], 0
	v_mfma_f32_16x16x32_bf16 v[90:93], v[170:173], v[202:205], 0
	v_mfma_f32_16x16x32_bf16 v[82:85], v[178:181], v[202:205], 0
	v_mfma_f32_16x16x32_bf16 v[74:77], v[170:173], v[210:213], 0
	v_mfma_f32_16x16x32_bf16 v[66:69], v[178:181], v[210:213], 0
	v_mfma_f32_16x16x32_bf16 v[122:125], v[174:177], v[190:193], v[122:125]
	v_mfma_f32_16x16x32_bf16 v[114:117], v[182:185], v[190:193], v[114:117]
	v_mfma_f32_16x16x32_bf16 v[106:109], v[174:177], v[198:201], v[106:109]
	v_mfma_f32_16x16x32_bf16 v[98:101], v[182:185], v[198:201], v[98:101]
	s_setprio 2
	s_barrier
	v_mfma_f32_16x16x32_bf16 v[90:93], v[174:177], v[206:209], v[90:93]
	v_mfma_f32_16x16x32_bf16 v[82:85], v[182:185], v[206:209], v[82:85]
	v_mfma_f32_16x16x32_bf16 v[74:77], v[174:177], v[214:217], v[74:77]
	v_mfma_f32_16x16x32_bf16 v[66:69], v[182:185], v[214:217], v[66:69]
	s_setprio 0
	s_nop 0
	s_add_i32 s45, s35, s26
	s_add_u32 s50, s22, 0x80
	s_addc_u32 s51, s23, 0
	s_add_u32 s52, s24, 0x80
	s_addc_u32 s53, s25, 0
	s_mov_b32 m0, s45
	ds_read_b128 v[186:189], v152 offset:16384
	ds_read_b128 v[190:193], v152 offset:17408
	ds_read_b128 v[194:197], v152 offset:18432
	ds_read_b128 v[198:201], v152 offset:19456
	ds_read_b128 v[202:205], v152 offset:20480
	ds_read_b128 v[206:209], v152 offset:21504
	ds_read_b128 v[210:213], v152 offset:22528
	ds_read_b128 v[214:217], v152 offset:23552
	global_load_lds_dwordx4 v134, s[22:23]
	s_add_i32 m0, s45, 0x2000
	s_add_u32 s46, s22, 0x40000
	s_addc_u32 s47, s23, 0
	s_add_i32 s45, s36, s26
	global_load_lds_dwordx4 v130, s[22:23]
	s_mov_b32 m0, s45
	s_nop 0
	global_load_lds_dwordx4 v134, s[46:47]
	s_add_i32 m0, s45, 0x2000
	s_nop 0
	global_load_lds_dwordx4 v130, s[46:47]
	s_mov_b32 m0, s27
	s_nop 0
	global_load_lds_dwordx4 v136, s[24:25]
	s_mov_b32 m0, s28
	s_nop 0
	global_load_lds_dwordx4 v132, s[24:25]
	s_nop 0
	s_waitcnt lgkmcnt(0)
	s_barrier
	s_setprio 1
	v_mfma_f32_16x16x32_bf16 v[62:65], v[154:157], v[186:189], 0
	v_mfma_f32_16x16x32_bf16 v[54:57], v[162:165], v[186:189], 0
	v_mfma_f32_16x16x32_bf16 v[46:49], v[154:157], v[194:197], 0
	v_mfma_f32_16x16x32_bf16 v[38:41], v[162:165], v[194:197], 0
	v_mfma_f32_16x16x32_bf16 v[30:33], v[154:157], v[202:205], 0
	v_mfma_f32_16x16x32_bf16 v[22:25], v[162:165], v[202:205], 0
	v_mfma_f32_16x16x32_bf16 v[14:17], v[154:157], v[210:213], 0
	v_mfma_f32_16x16x32_bf16 v[6:9], v[162:165], v[210:213], 0
	v_mfma_f32_16x16x32_bf16 v[62:65], v[158:161], v[190:193], v[62:65]
	v_mfma_f32_16x16x32_bf16 v[54:57], v[166:169], v[190:193], v[54:57]
	v_mfma_f32_16x16x32_bf16 v[46:49], v[158:161], v[198:201], v[46:49]
	v_mfma_f32_16x16x32_bf16 v[38:41], v[166:169], v[198:201], v[38:41]
	v_mfma_f32_16x16x32_bf16 v[30:33], v[158:161], v[206:209], v[30:33]
	v_mfma_f32_16x16x32_bf16 v[22:25], v[166:169], v[206:209], v[22:25]
	v_mfma_f32_16x16x32_bf16 v[14:17], v[158:161], v[214:217], v[14:17]
	v_mfma_f32_16x16x32_bf16 v[6:9], v[166:169], v[214:217], v[6:9]
	v_mfma_f32_16x16x32_bf16 v[58:61], v[170:173], v[186:189], 0
	v_mfma_f32_16x16x32_bf16 v[50:53], v[178:181], v[186:189], 0
	v_mfma_f32_16x16x32_bf16 v[42:45], v[170:173], v[194:197], 0
	v_mfma_f32_16x16x32_bf16 v[34:37], v[178:181], v[194:197], 0
	v_mfma_f32_16x16x32_bf16 v[26:29], v[170:173], v[202:205], 0
	v_mfma_f32_16x16x32_bf16 v[18:21], v[178:181], v[202:205], 0
	v_mfma_f32_16x16x32_bf16 v[10:13], v[170:173], v[210:213], 0
	v_mfma_f32_16x16x32_bf16 v[2:5], v[178:181], v[210:213], 0
	v_mfma_f32_16x16x32_bf16 v[58:61], v[174:177], v[190:193], v[58:61]
	v_mfma_f32_16x16x32_bf16 v[50:53], v[182:185], v[190:193], v[50:53]
	v_mfma_f32_16x16x32_bf16 v[42:45], v[174:177], v[198:201], v[42:45]
	v_mfma_f32_16x16x32_bf16 v[34:37], v[182:185], v[198:201], v[34:37]
	s_setprio 2
	s_barrier
	v_mfma_f32_16x16x32_bf16 v[26:29], v[174:177], v[206:209], v[26:29]
	v_mfma_f32_16x16x32_bf16 v[18:21], v[182:185], v[206:209], v[18:21]
	v_mfma_f32_16x16x32_bf16 v[10:13], v[174:177], v[214:217], v[10:13]
	v_mfma_f32_16x16x32_bf16 v[2:5], v[182:185], v[214:217], v[2:5]
	s_setprio 0
	s_nop 0
	s_add_i32 s45, 0, 0x18000
	s_add_i32 s46, 0, 0x1c000
	ds_read_b128 v[154:157], v229 offset:32768
	ds_read_b128 v[158:161], v229 offset:33792
	ds_read_b128 v[162:165], v229 offset:34816
	ds_read_b128 v[166:169], v229 offset:35840
	ds_read_b128 v[170:173], v229 offset:49152
	ds_read_b128 v[174:177], v229 offset:50176
	ds_read_b128 v[178:181], v229 offset:51200
	ds_read_b128 v[182:185], v229 offset:52224
	s_add_u32 s24, s24, 0x40000
	s_addc_u32 s25, s25, 0
	s_mov_b32 m0, s29
	ds_read_b128 v[186:189], v152 offset:32768
	ds_read_b128 v[190:193], v152 offset:33792
	ds_read_b128 v[194:197], v152 offset:34816
	ds_read_b128 v[198:201], v152 offset:35840
	ds_read_b128 v[202:205], v152 offset:36864
	ds_read_b128 v[206:209], v152 offset:37888
	ds_read_b128 v[210:213], v152 offset:38912
	ds_read_b128 v[214:217], v152 offset:39936
	global_load_lds_dwordx4 v136, s[24:25]
	s_mov_b32 m0, s30
	s_nop 0
	global_load_lds_dwordx4 v132, s[24:25]
	s_waitcnt vmcnt(8)
	s_waitcnt lgkmcnt(0)
	s_barrier
	s_setprio 1
	v_mfma_f32_16x16x32_bf16 v[126:129], v[154:157], v[186:189], v[126:129]
	v_mfma_f32_16x16x32_bf16 v[118:121], v[162:165], v[186:189], v[118:121]
	v_mfma_f32_16x16x32_bf16 v[110:113], v[154:157], v[194:197], v[110:113]
	v_mfma_f32_16x16x32_bf16 v[102:105], v[162:165], v[194:197], v[102:105]
	v_mfma_f32_16x16x32_bf16 v[94:97], v[154:157], v[202:205], v[94:97]
	v_mfma_f32_16x16x32_bf16 v[86:89], v[162:165], v[202:205], v[86:89]
	v_mfma_f32_16x16x32_bf16 v[78:81], v[154:157], v[210:213], v[78:81]
	v_mfma_f32_16x16x32_bf16 v[70:73], v[162:165], v[210:213], v[70:73]
	v_mfma_f32_16x16x32_bf16 v[126:129], v[158:161], v[190:193], v[126:129]
	v_mfma_f32_16x16x32_bf16 v[118:121], v[166:169], v[190:193], v[118:121]
	v_mfma_f32_16x16x32_bf16 v[110:113], v[158:161], v[198:201], v[110:113]
	v_mfma_f32_16x16x32_bf16 v[102:105], v[166:169], v[198:201], v[102:105]
	v_mfma_f32_16x16x32_bf16 v[94:97], v[158:161], v[206:209], v[94:97]
	v_mfma_f32_16x16x32_bf16 v[86:89], v[166:169], v[206:209], v[86:89]
	v_mfma_f32_16x16x32_bf16 v[78:81], v[158:161], v[214:217], v[78:81]
	v_mfma_f32_16x16x32_bf16 v[70:73], v[166:169], v[214:217], v[70:73]
	v_mfma_f32_16x16x32_bf16 v[122:125], v[170:173], v[186:189], v[122:125]
	v_mfma_f32_16x16x32_bf16 v[114:117], v[178:181], v[186:189], v[114:117]
	v_mfma_f32_16x16x32_bf16 v[106:109], v[170:173], v[194:197], v[106:109]
	v_mfma_f32_16x16x32_bf16 v[98:101], v[178:181], v[194:197], v[98:101]
	v_mfma_f32_16x16x32_bf16 v[90:93], v[170:173], v[202:205], v[90:93]
	v_mfma_f32_16x16x32_bf16 v[82:85], v[178:181], v[202:205], v[82:85]
	v_mfma_f32_16x16x32_bf16 v[74:77], v[170:173], v[210:213], v[74:77]
	v_mfma_f32_16x16x32_bf16 v[66:69], v[178:181], v[210:213], v[66:69]
	v_mfma_f32_16x16x32_bf16 v[122:125], v[174:177], v[190:193], v[122:125]
	v_mfma_f32_16x16x32_bf16 v[114:117], v[182:185], v[190:193], v[114:117]
	v_mfma_f32_16x16x32_bf16 v[106:109], v[174:177], v[198:201], v[106:109]
	v_mfma_f32_16x16x32_bf16 v[98:101], v[182:185], v[198:201], v[98:101]
	s_setprio 2
	s_barrier
	v_mfma_f32_16x16x32_bf16 v[90:93], v[174:177], v[206:209], v[90:93]
	v_mfma_f32_16x16x32_bf16 v[82:85], v[182:185], v[206:209], v[82:85]
	v_mfma_f32_16x16x32_bf16 v[74:77], v[174:177], v[214:217], v[74:77]
	v_mfma_f32_16x16x32_bf16 v[66:69], v[182:185], v[214:217], v[66:69]
	s_setprio 0
	s_nop 0
	s_add_i32 s24, s45, s26
	s_mov_b32 m0, s24
	ds_read_b128 v[186:189], v152 offset:49152
	ds_read_b128 v[190:193], v152 offset:50176
	ds_read_b128 v[194:197], v152 offset:51200
	ds_read_b128 v[198:201], v152 offset:52224
	ds_read_b128 v[202:205], v152 offset:53248
	ds_read_b128 v[206:209], v152 offset:54272
	ds_read_b128 v[210:213], v152 offset:55296
	ds_read_b128 v[214:217], v152 offset:56320
	global_load_lds_dwordx4 v134, s[50:51]
	s_add_i32 m0, s24, 0x2000
	s_add_u32 s22, s22, 0x40080
	s_addc_u32 s23, s23, 0
	s_add_i32 s24, s46, s26
	global_load_lds_dwordx4 v130, s[50:51]
	s_mov_b32 m0, s24
	s_nop 0
	global_load_lds_dwordx4 v134, s[22:23]
	s_add_i32 m0, s24, 0x2000
	s_nop 0
	global_load_lds_dwordx4 v130, s[22:23]
	s_mov_b32 m0, s33
	s_nop 0
	global_load_lds_dwordx4 v136, s[52:53]
	s_mov_b32 m0, s34
	s_nop 0
	global_load_lds_dwordx4 v132, s[52:53]
	s_waitcnt vmcnt(8)
	s_waitcnt lgkmcnt(0)
	s_barrier
	s_setprio 1
	v_mfma_f32_16x16x32_bf16 v[62:65], v[154:157], v[186:189], v[62:65]
	v_mfma_f32_16x16x32_bf16 v[54:57], v[162:165], v[186:189], v[54:57]
	v_mfma_f32_16x16x32_bf16 v[46:49], v[154:157], v[194:197], v[46:49]
	v_mfma_f32_16x16x32_bf16 v[38:41], v[162:165], v[194:197], v[38:41]
	v_mfma_f32_16x16x32_bf16 v[30:33], v[154:157], v[202:205], v[30:33]
	v_mfma_f32_16x16x32_bf16 v[22:25], v[162:165], v[202:205], v[22:25]
	v_mfma_f32_16x16x32_bf16 v[14:17], v[154:157], v[210:213], v[14:17]
	v_mfma_f32_16x16x32_bf16 v[6:9], v[162:165], v[210:213], v[6:9]
	v_mfma_f32_16x16x32_bf16 v[62:65], v[158:161], v[190:193], v[62:65]
	v_mfma_f32_16x16x32_bf16 v[54:57], v[166:169], v[190:193], v[54:57]
	v_mfma_f32_16x16x32_bf16 v[46:49], v[158:161], v[198:201], v[46:49]
	v_mfma_f32_16x16x32_bf16 v[38:41], v[166:169], v[198:201], v[38:41]
	v_mfma_f32_16x16x32_bf16 v[30:33], v[158:161], v[206:209], v[30:33]
	v_mfma_f32_16x16x32_bf16 v[22:25], v[166:169], v[206:209], v[22:25]
	v_mfma_f32_16x16x32_bf16 v[14:17], v[158:161], v[214:217], v[14:17]
	v_mfma_f32_16x16x32_bf16 v[6:9], v[166:169], v[214:217], v[6:9]
	v_mfma_f32_16x16x32_bf16 v[58:61], v[170:173], v[186:189], v[58:61]
	v_mfma_f32_16x16x32_bf16 v[50:53], v[178:181], v[186:189], v[50:53]
	v_mfma_f32_16x16x32_bf16 v[42:45], v[170:173], v[194:197], v[42:45]
	v_mfma_f32_16x16x32_bf16 v[34:37], v[178:181], v[194:197], v[34:37]
	v_mfma_f32_16x16x32_bf16 v[26:29], v[170:173], v[202:205], v[26:29]
	v_mfma_f32_16x16x32_bf16 v[18:21], v[178:181], v[202:205], v[18:21]
	v_mfma_f32_16x16x32_bf16 v[10:13], v[170:173], v[210:213], v[10:13]
	v_mfma_f32_16x16x32_bf16 v[2:5], v[178:181], v[210:213], v[2:5]
	v_mfma_f32_16x16x32_bf16 v[58:61], v[174:177], v[190:193], v[58:61]
	v_mfma_f32_16x16x32_bf16 v[50:53], v[182:185], v[190:193], v[50:53]
	v_mfma_f32_16x16x32_bf16 v[42:45], v[174:177], v[198:201], v[42:45]
	v_mfma_f32_16x16x32_bf16 v[34:37], v[182:185], v[198:201], v[34:37]
	s_setprio 2
	s_barrier
	v_mfma_f32_16x16x32_bf16 v[26:29], v[174:177], v[206:209], v[26:29]
	v_mfma_f32_16x16x32_bf16 v[18:21], v[182:185], v[206:209], v[18:21]
	v_mfma_f32_16x16x32_bf16 v[10:13], v[174:177], v[214:217], v[10:13]
	v_mfma_f32_16x16x32_bf16 v[2:5], v[182:185], v[214:217], v[2:5]
	s_setprio 0
	s_nop 0
	s_add_i32 s44, s44, 2
	s_add_u32 s20, s20, 0x100
	s_addc_u32 s21, s21, 0
	s_cmp_gt_u32 s44, 13
	s_cbranch_scc1 .LBB0_948
	s_branch .LBB0_946

.LBB0_950:
	s_waitcnt vmcnt(0)
	ds_read2_b32 v[156:157], v150 offset1:16
	v_mul_f32_e32 v122, v126, v122
	v_mul_f32_e32 v123, v127, v123
	v_mul_f32_e32 v124, v128, v124
	v_mul_f32_e32 v125, v129, v125
	s_waitcnt lgkmcnt(0)
	v_fmamk_f32 v155, v156, 0x3a800000, v153
	v_rsq_f32_e32 v156, v155
	v_mul_f32_e32 v114, v118, v114
	v_mul_f32_e32 v115, v119, v115
	v_mul_f32_e32 v116, v120, v116
	v_mul_f32_e32 v156, 0xbfb8aa3b, v156
	v_mul_f32_e32 v158, v126, v156
	v_exp_f32_e32 v160, v158
	v_mul_f32_e32 v159, v127, v156
	v_mul_f32_e32 v127, v129, v156
	v_exp_f32_e32 v127, v127
	v_fma_f32 v126, v160, v155, v155
	v_rcp_f32_e32 v126, v126
	v_exp_f32_e32 v159, v159
	v_fma_f32 v127, v127, v155, v155
	v_rcp_f32_e32 v127, v127
	v_mul_f32_e32 v122, v122, v126
	v_mul_f32_e32 v126, v128, v156
	v_exp_f32_e32 v126, v126
	v_mul_f32_e32 v128, v118, v156
	v_exp_f32_e32 v128, v128
	v_mul_f32_e32 v125, v125, v127
	v_fma_f32 v126, v126, v155, v155
	v_rcp_f32_e32 v126, v126
	v_mul_f32_e32 v127, v119, v156
	v_exp_f32_e32 v127, v127
	v_mul_f32_e32 v119, v120, v156
	v_mul_f32_e32 v124, v124, v126
	v_fma_f32 v126, v128, v155, v155
	v_rcp_f32_e32 v126, v126
	v_fma_f32 v118, v127, v155, v155
	v_rcp_f32_e32 v118, v118
	v_exp_f32_e32 v119, v119
	v_mul_f32_e32 v114, v114, v126
	v_mul_f32_e32 v126, v121, v156
	v_exp_f32_e32 v126, v126
	v_fma_f32 v159, v159, v155, v155
	v_mul_f32_e32 v115, v115, v118
	v_fma_f32 v118, v119, v155, v155
	v_fmac_f32_e32 v155, v126, v155
	v_rcp_f32_e32 v160, v159
	v_rcp_f32_e32 v118, v118
	v_rcp_f32_e32 v119, v155
	v_mul_f32_e32 v117, v121, v117
	ds_read2_b32 v[146:147], v150 offset0:32 offset1:48
	ds_read2_b32 v[144:145], v150 offset0:128 offset1:144
	ds_read2_b32 v[142:143], v150 offset0:160 offset1:176
	v_mul_f32_e32 v123, v123, v160
	v_mul_f32_e32 v116, v116, v118
	v_mul_f32_e32 v117, v117, v119
	v_cvt_pk_bf16_f32 v118, v122, v123
	v_cvt_pk_bf16_f32 v119, v124, v125
	v_fmamk_f32 v124, v157, 0x3a800000, v153
	v_rsq_f32_e32 v125, v124
	v_mul_f32_e32 v106, v110, v106
	v_mul_f32_e32 v107, v111, v107
	v_mul_f32_e32 v108, v112, v108
	v_mul_f32_e32 v125, 0xbfb8aa3b, v125
	v_mul_f32_e32 v126, v110, v125
	v_mul_f32_e32 v127, v111, v125
	v_mul_f32_e32 v110, v112, v125
	v_mul_f32_e32 v111, v113, v125
	v_exp_f32_e32 v110, v110
	v_exp_f32_e32 v111, v111
	v_mul_f32_e32 v112, v102, v125
	v_exp_f32_e32 v112, v112
	v_fma_f32 v110, v110, v124, v124
	v_fma_f32 v111, v111, v124, v124
	v_rcp_f32_e32 v110, v110
	v_rcp_f32_e32 v111, v111
	v_mul_f32_e32 v109, v113, v109
	v_mul_f32_e32 v98, v102, v98
	v_mul_f32_e32 v108, v108, v110
	v_mul_f32_e32 v109, v109, v111
	v_fma_f32 v110, v112, v124, v124
	v_mul_f32_e32 v111, v103, v125
	v_rcp_f32_e32 v110, v110
	v_exp_f32_e32 v111, v111
	v_lshl_or_b32 v158, s38, 7, v151
	v_exp_f32_e32 v126, v126
	v_mul_f32_e32 v102, v98, v110
	v_mul_f32_e32 v98, v103, v99
	v_fma_f32 v99, v111, v124, v124
	v_mul_f32_e32 v103, v104, v125
	v_rcp_f32_e32 v99, v99
	v_exp_f32_e32 v103, v103
	v_exp_f32_e32 v127, v127
	v_mul_f32_e32 v110, v105, v125
	v_mul_f32_e32 v111, v98, v99
	v_fma_f32 v98, v103, v124, v124
	v_add_u32_e32 v154, s11, v148
	v_ashrrev_i32_e32 v159, 31, v158
	v_cvt_pk_bf16_f32 v120, v114, v115
	v_mov_b64_e32 v[114:115], s[84:85]
	v_exp_f32_e32 v110, v110
	v_rcp_f32_e32 v98, v98
	v_cvt_pk_bf16_f32 v121, v116, v117
	v_mad_i64_i32 v[122:123], s[18:19], v154, s37, v[114:115]
	v_lshlrev_b64 v[116:117], 1, v[158:159]
	v_lshl_add_u64 v[122:123], v[122:123], 0, v[116:117]
	global_store_dwordx4 v[122:123], v[118:121], off
	v_mul_f32_e32 v100, v104, v100
	s_waitcnt lgkmcnt(0)
	v_fmamk_f32 v104, v146, 0x3a800000, v153
	v_fma_f32 v118, v126, v124, v124
	v_fma_f32 v119, v127, v124, v124
	v_rcp_f32_e32 v118, v118
	v_rcp_f32_e32 v119, v119
	v_fmac_f32_e32 v124, v110, v124
	v_mul_f32_e32 v103, v100, v98
	v_mul_f32_e32 v98, v105, v101
	v_rsq_f32_e32 v105, v104
	v_rcp_f32_e32 v99, v124
	v_mul_f32_e32 v106, v106, v118
	v_mul_f32_e32 v107, v107, v119
	v_mul_f32_e32 v105, 0xbfb8aa3b, v105
	v_mul_f32_e32 v101, v98, v99
	v_cvt_pk_bf16_f32 v98, v106, v107
	v_mul_f32_e32 v106, v94, v105
	v_mul_f32_e32 v107, v95, v105
	v_mul_f32_e32 v90, v94, v90
	v_mul_f32_e32 v91, v95, v91
	v_mul_f32_e32 v94, v96, v105
	v_mul_f32_e32 v95, v97, v105
	v_exp_f32_e32 v94, v94
	v_exp_f32_e32 v95, v95
	v_mul_f32_e32 v92, v96, v92
	v_mul_f32_e32 v96, v86, v105
	v_fma_f32 v94, v94, v104, v104
	v_fma_f32 v95, v95, v104, v104
	v_rcp_f32_e32 v94, v94
	v_rcp_f32_e32 v95, v95
	v_exp_f32_e32 v96, v96
	v_mul_f32_e32 v93, v97, v93
	v_mul_f32_e32 v92, v92, v94
	v_mul_f32_e32 v93, v93, v95
	v_fma_f32 v94, v96, v104, v104
	v_mul_f32_e32 v95, v87, v105
	v_rcp_f32_e32 v94, v94
	v_exp_f32_e32 v95, v95
	v_mul_f32_e32 v82, v86, v82
	v_exp_f32_e32 v106, v106
	v_mul_f32_e32 v86, v82, v94
	v_mul_f32_e32 v82, v87, v83
	v_fma_f32 v83, v95, v104, v104
	v_mul_f32_e32 v87, v88, v105
	v_rcp_f32_e32 v83, v83
	v_exp_f32_e32 v87, v87
	v_exp_f32_e32 v107, v107
	v_mul_f32_e32 v94, v89, v105
	v_mul_f32_e32 v95, v82, v83
	v_fma_f32 v82, v87, v104, v104
	v_cvt_pk_bf16_f32 v99, v108, v109
	v_cvt_pk_bf16_f32 v100, v102, v111
	v_or_b32_e32 v102, 16, v154
	v_exp_f32_e32 v94, v94
	v_rcp_f32_e32 v82, v82
	v_cvt_pk_bf16_f32 v101, v103, v101
	v_mad_i64_i32 v[102:103], s[18:19], v102, s37, v[114:115]
	v_lshl_add_u64 v[102:103], v[102:103], 0, v[116:117]
	global_store_dwordx4 v[102:103], v[98:101], off
	v_mul_f32_e32 v84, v88, v84
	v_fmamk_f32 v88, v147, 0x3a800000, v153
	v_fma_f32 v98, v106, v104, v104
	v_fma_f32 v99, v107, v104, v104
	v_rcp_f32_e32 v98, v98
	v_rcp_f32_e32 v99, v99
	v_fmac_f32_e32 v104, v94, v104
	v_mul_f32_e32 v87, v84, v82
	v_mul_f32_e32 v82, v89, v85
	v_rsq_f32_e32 v89, v88
	v_rcp_f32_e32 v83, v104
	v_mul_f32_e32 v90, v90, v98
	v_mul_f32_e32 v91, v91, v99
	v_mul_f32_e32 v89, 0xbfb8aa3b, v89
	v_mul_f32_e32 v85, v82, v83
	v_cvt_pk_bf16_f32 v82, v90, v91
	v_mul_f32_e32 v90, v78, v89
	v_mul_f32_e32 v91, v79, v89
	v_mul_f32_e32 v74, v78, v74
	v_mul_f32_e32 v75, v79, v75
	v_mul_f32_e32 v78, v80, v89
	v_mul_f32_e32 v79, v81, v89
	v_exp_f32_e32 v78, v78
	v_exp_f32_e32 v79, v79
	v_mul_f32_e32 v76, v80, v76
	v_mul_f32_e32 v80, v70, v89
	v_fma_f32 v78, v78, v88, v88
	v_fma_f32 v79, v79, v88, v88
	v_rcp_f32_e32 v78, v78
	v_rcp_f32_e32 v79, v79
	v_exp_f32_e32 v80, v80
	v_mul_f32_e32 v77, v81, v77
	v_mul_f32_e32 v76, v76, v78
	v_mul_f32_e32 v77, v77, v79
	v_fma_f32 v78, v80, v88, v88
	v_mul_f32_e32 v79, v71, v89
	v_rcp_f32_e32 v78, v78
	v_exp_f32_e32 v79, v79
	v_mul_f32_e32 v66, v70, v66
	v_exp_f32_e32 v90, v90
	v_mul_f32_e32 v70, v66, v78
	v_mul_f32_e32 v66, v71, v67
	v_fma_f32 v67, v79, v88, v88
	v_mul_f32_e32 v71, v72, v89
	v_rcp_f32_e32 v67, v67
	v_exp_f32_e32 v71, v71
	v_mul_f32_e32 v78, v73, v89
	v_exp_f32_e32 v91, v91
	v_exp_f32_e32 v78, v78
	v_cvt_pk_bf16_f32 v83, v92, v93
	v_cvt_pk_bf16_f32 v84, v86, v95
	v_or_b32_e32 v86, 32, v154
	v_cvt_pk_bf16_f32 v85, v87, v85
	v_mad_i64_i32 v[86:87], s[18:19], v86, s37, v[114:115]
	v_lshl_add_u64 v[86:87], v[86:87], 0, v[116:117]
	v_mul_f32_e32 v79, v66, v67
	v_fma_f32 v66, v71, v88, v88
	global_store_dwordx4 v[86:87], v[82:85], off
	v_rcp_f32_e32 v66, v66
	v_mul_f32_e32 v68, v72, v68
	v_fma_f32 v82, v90, v88, v88
	v_fma_f32 v83, v91, v88, v88
	v_fmac_f32_e32 v88, v78, v88
	v_rcp_f32_e32 v82, v82
	v_rcp_f32_e32 v83, v83
	v_rcp_f32_e32 v67, v88
	v_fmamk_f32 v72, v144, 0x3a800000, v153
	v_mul_f32_e32 v71, v68, v66
	v_mul_f32_e32 v66, v73, v69
	v_rsq_f32_e32 v73, v72
	v_mul_f32_e32 v74, v74, v82
	v_mul_f32_e32 v75, v75, v83
	v_mul_f32_e32 v69, v66, v67
	v_cvt_pk_bf16_f32 v66, v74, v75
	v_cvt_pk_bf16_f32 v67, v76, v77
	v_cvt_pk_bf16_f32 v68, v70, v79
	v_or_b32_e32 v70, 48, v154
	v_cvt_pk_bf16_f32 v69, v71, v69
	v_mad_i64_i32 v[70:71], s[18:19], v70, s37, v[114:115]
	v_lshl_add_u64 v[70:71], v[70:71], 0, v[116:117]
	global_store_dwordx4 v[70:71], v[66:69], off
	v_mul_f32_e32 v58, v62, v58
	v_mul_f32_e32 v59, v63, v59
	v_mul_f32_e32 v66, 0xbfb8aa3b, v73
	v_mul_f32_e32 v67, v62, v66
	v_mul_f32_e32 v68, v63, v66
	v_mul_f32_e32 v62, v64, v66
	v_mul_f32_e32 v63, v65, v66
	v_exp_f32_e32 v62, v62
	v_exp_f32_e32 v63, v63
	v_mul_f32_e32 v60, v64, v60
	v_mul_f32_e32 v64, v54, v66
	v_fma_f32 v62, v62, v72, v72
	v_fma_f32 v63, v63, v72, v72
	v_rcp_f32_e32 v62, v62
	v_rcp_f32_e32 v63, v63
	v_exp_f32_e32 v64, v64
	v_mul_f32_e32 v61, v65, v61
	v_mul_f32_e32 v60, v60, v62
	v_mul_f32_e32 v61, v61, v63
	v_fma_f32 v62, v64, v72, v72
	v_mul_f32_e32 v63, v55, v66
	v_rcp_f32_e32 v62, v62
	v_exp_f32_e32 v63, v63
	v_mul_f32_e32 v50, v54, v50
	v_exp_f32_e32 v67, v67
	v_mul_f32_e32 v54, v50, v62
	v_mul_f32_e32 v50, v55, v51
	v_fma_f32 v51, v63, v72, v72
	v_mul_f32_e32 v55, v56, v66
	v_rcp_f32_e32 v51, v51
	v_exp_f32_e32 v55, v55
	v_exp_f32_e32 v68, v68
	v_mul_f32_e32 v62, v57, v66
	v_mul_f32_e32 v63, v50, v51
	v_fma_f32 v50, v55, v72, v72
	v_exp_f32_e32 v62, v62
	v_rcp_f32_e32 v50, v50
	v_fma_f32 v67, v67, v72, v72
	v_fma_f32 v68, v68, v72, v72
	v_mul_f32_e32 v52, v56, v52
	v_fmamk_f32 v56, v145, 0x3a800000, v153
	v_rcp_f32_e32 v67, v67
	v_rcp_f32_e32 v68, v68
	v_fmac_f32_e32 v72, v62, v72
	v_mul_f32_e32 v55, v52, v50
	v_mul_f32_e32 v50, v57, v53
	v_rsq_f32_e32 v57, v56
	v_rcp_f32_e32 v51, v72
	v_mul_f32_e32 v58, v58, v67
	v_mul_f32_e32 v59, v59, v68
	v_mul_f32_e32 v57, 0xbfb8aa3b, v57
	v_mul_f32_e32 v53, v50, v51
	v_cvt_pk_bf16_f32 v50, v58, v59
	v_mul_f32_e32 v58, v46, v57
	v_mul_f32_e32 v59, v47, v57
	v_mul_f32_e32 v42, v46, v42
	v_mul_f32_e32 v43, v47, v43
	v_mul_f32_e32 v46, v48, v57
	v_mul_f32_e32 v47, v49, v57
	v_exp_f32_e32 v46, v46
	v_exp_f32_e32 v47, v47
	v_mul_f32_e32 v44, v48, v44
	v_mul_f32_e32 v48, v38, v57
	v_fma_f32 v46, v46, v56, v56
	v_fma_f32 v47, v47, v56, v56
	v_rcp_f32_e32 v46, v46
	v_rcp_f32_e32 v47, v47
	v_exp_f32_e32 v48, v48
	v_mul_f32_e32 v45, v49, v45
	v_mul_f32_e32 v44, v44, v46
	v_mul_f32_e32 v45, v45, v47
	v_fma_f32 v46, v48, v56, v56
	v_mul_f32_e32 v47, v39, v57
	v_rcp_f32_e32 v46, v46
	v_exp_f32_e32 v47, v47
	v_mul_f32_e32 v34, v38, v34
	v_exp_f32_e32 v58, v58
	v_mul_f32_e32 v38, v34, v46
	v_mul_f32_e32 v34, v39, v35
	v_fma_f32 v35, v47, v56, v56
	v_mul_f32_e32 v39, v40, v57
	v_rcp_f32_e32 v35, v35
	v_exp_f32_e32 v39, v39
	v_exp_f32_e32 v59, v59
	v_mul_f32_e32 v46, v41, v57
	v_mul_f32_e32 v47, v34, v35
	v_fma_f32 v34, v39, v56, v56
	v_add_u32_e32 v69, 0x80, v154
	v_exp_f32_e32 v46, v46
	v_rcp_f32_e32 v34, v34
	v_cvt_pk_bf16_f32 v51, v60, v61
	v_cvt_pk_bf16_f32 v52, v54, v63
	v_cvt_pk_bf16_f32 v53, v55, v53
	v_mad_i64_i32 v[54:55], s[18:19], v69, s37, v[114:115]
	v_lshl_add_u64 v[54:55], v[54:55], 0, v[116:117]
	global_store_dwordx4 v[54:55], v[50:53], off
	v_mul_f32_e32 v36, v40, v36
	v_fmamk_f32 v40, v142, 0x3a800000, v153
	v_fma_f32 v50, v58, v56, v56
	v_fma_f32 v51, v59, v56, v56
	v_rcp_f32_e32 v50, v50
	v_rcp_f32_e32 v51, v51
	v_fmac_f32_e32 v56, v46, v56
	v_mul_f32_e32 v39, v36, v34
	v_mul_f32_e32 v34, v41, v37
	v_rsq_f32_e32 v41, v40
	v_rcp_f32_e32 v35, v56
	v_mul_f32_e32 v42, v42, v50
	v_mul_f32_e32 v43, v43, v51
	v_mul_f32_e32 v41, 0xbfb8aa3b, v41
	v_mul_f32_e32 v37, v34, v35
	v_cvt_pk_bf16_f32 v34, v42, v43
	v_mul_f32_e32 v42, v30, v41
	v_mul_f32_e32 v43, v31, v41
	v_mul_f32_e32 v26, v30, v26
	v_mul_f32_e32 v27, v31, v27
	v_mul_f32_e32 v30, v32, v41
	v_mul_f32_e32 v31, v33, v41
	v_exp_f32_e32 v30, v30
	v_exp_f32_e32 v31, v31
	v_mul_f32_e32 v28, v32, v28
	v_mul_f32_e32 v32, v22, v41
	v_fma_f32 v30, v30, v40, v40
	v_fma_f32 v31, v31, v40, v40
	v_rcp_f32_e32 v30, v30
	v_rcp_f32_e32 v31, v31
	v_exp_f32_e32 v32, v32
	v_mul_f32_e32 v29, v33, v29
	v_mul_f32_e32 v28, v28, v30
	v_mul_f32_e32 v29, v29, v31
	v_fma_f32 v30, v32, v40, v40
	v_mul_f32_e32 v31, v23, v41
	v_rcp_f32_e32 v30, v30
	v_exp_f32_e32 v31, v31
	v_mul_f32_e32 v18, v22, v18
	v_exp_f32_e32 v42, v42
	v_mul_f32_e32 v22, v18, v30
	v_mul_f32_e32 v18, v23, v19
	v_fma_f32 v19, v31, v40, v40
	v_mul_f32_e32 v23, v24, v41
	v_rcp_f32_e32 v19, v19
	v_exp_f32_e32 v23, v23
	v_exp_f32_e32 v43, v43
	v_mul_f32_e32 v30, v25, v41
	v_mul_f32_e32 v31, v18, v19
	v_fma_f32 v18, v23, v40, v40
	v_cvt_pk_bf16_f32 v35, v44, v45
	v_cvt_pk_bf16_f32 v36, v38, v47
	v_add_u32_e32 v38, 0x90, v154
	v_exp_f32_e32 v30, v30
	v_rcp_f32_e32 v18, v18
	v_cvt_pk_bf16_f32 v37, v39, v37
	v_mad_i64_i32 v[38:39], s[18:19], v38, s37, v[114:115]
	v_lshl_add_u64 v[38:39], v[38:39], 0, v[116:117]
	global_store_dwordx4 v[38:39], v[34:37], off
	v_mul_f32_e32 v20, v24, v20
	v_fmamk_f32 v24, v143, 0x3a800000, v153
	v_fma_f32 v34, v42, v40, v40
	v_fma_f32 v35, v43, v40, v40
	v_rcp_f32_e32 v34, v34
	v_rcp_f32_e32 v35, v35
	v_fmac_f32_e32 v40, v30, v40
	v_mul_f32_e32 v23, v20, v18
	v_mul_f32_e32 v18, v25, v21
	v_rsq_f32_e32 v25, v24
	v_rcp_f32_e32 v19, v40
	v_mul_f32_e32 v26, v26, v34
	v_mul_f32_e32 v27, v27, v35
	v_mul_f32_e32 v25, 0xbfb8aa3b, v25
	v_mul_f32_e32 v21, v18, v19
	v_cvt_pk_bf16_f32 v18, v26, v27
	v_mul_f32_e32 v26, v14, v25
	v_mul_f32_e32 v27, v15, v25
	v_mul_f32_e32 v10, v14, v10
	v_mul_f32_e32 v11, v15, v11
	v_mul_f32_e32 v14, v16, v25
	v_mul_f32_e32 v15, v17, v25
	v_exp_f32_e32 v14, v14
	v_exp_f32_e32 v15, v15
	v_mul_f32_e32 v12, v16, v12
	v_mul_f32_e32 v16, v6, v25
	v_fma_f32 v14, v14, v24, v24
	v_fma_f32 v15, v15, v24, v24
	v_rcp_f32_e32 v14, v14
	v_rcp_f32_e32 v15, v15
	v_exp_f32_e32 v16, v16
	v_mul_f32_e32 v13, v17, v13
	v_mul_f32_e32 v12, v12, v14
	v_mul_f32_e32 v13, v13, v15
	v_fma_f32 v14, v16, v24, v24
	v_mul_f32_e32 v15, v7, v25
	v_rcp_f32_e32 v14, v14
	v_exp_f32_e32 v15, v15
	v_mul_f32_e32 v2, v6, v2
	v_exp_f32_e32 v26, v26
	v_mul_f32_e32 v6, v2, v14
	v_mul_f32_e32 v2, v7, v3
	v_fma_f32 v3, v15, v24, v24
	v_mul_f32_e32 v7, v8, v25
	v_rcp_f32_e32 v3, v3
	v_exp_f32_e32 v7, v7
	v_mul_f32_e32 v14, v9, v25
	v_exp_f32_e32 v27, v27
	v_exp_f32_e32 v14, v14
	v_cvt_pk_bf16_f32 v19, v28, v29
	v_cvt_pk_bf16_f32 v20, v22, v31
	v_add_u32_e32 v22, 0xa0, v154
	v_cvt_pk_bf16_f32 v21, v23, v21
	v_mad_i64_i32 v[22:23], s[18:19], v22, s37, v[114:115]
	v_lshl_add_u64 v[22:23], v[22:23], 0, v[116:117]
	v_mul_f32_e32 v15, v2, v3
	v_fma_f32 v2, v7, v24, v24
	global_store_dwordx4 v[22:23], v[18:21], off
	v_rcp_f32_e32 v2, v2
	v_mul_f32_e32 v4, v8, v4
	v_fma_f32 v18, v26, v24, v24
	v_fma_f32 v19, v27, v24, v24
	v_fmac_f32_e32 v24, v14, v24
	v_rcp_f32_e32 v18, v18
	v_rcp_f32_e32 v19, v19
	v_rcp_f32_e32 v3, v24
	v_mul_f32_e32 v7, v4, v2
	v_mul_f32_e32 v2, v9, v5
	v_mul_f32_e32 v10, v10, v18
	v_mul_f32_e32 v11, v11, v19
	v_mul_f32_e32 v5, v2, v3
	v_cvt_pk_bf16_f32 v2, v10, v11
	v_cvt_pk_bf16_f32 v3, v12, v13
	v_cvt_pk_bf16_f32 v4, v6, v15
	v_add_u32_e32 v6, 0xb0, v154
	v_cvt_pk_bf16_f32 v5, v7, v5
	v_mad_i64_i32 v[6:7], s[18:19], v6, s37, v[114:115]
	v_lshl_add_u64 v[6:7], v[6:7], 0, v[116:117]
	s_andn2_b64 vcc, exec, s[12:13]
	s_mov_b64 s[12:13], -1
	global_store_dwordx4 v[6:7], v[2:5], off
	s_cbranch_vccnz .LBB0_941
	s_andn2_b64 vcc, exec, s[0:1]
	s_cbranch_vccnz .LBB0_940
	s_barrier
	s_branch .LBB0_940
